# attnA: per-tile lazy-rescale test (row-max tree) skipped when the phase prologue proves from max|q_gain|*max|k_gain| that exp2 cannot overflow; checked loop kept as fallback
# speedup vs baseline: 1.0059x; 1.0059x over previous
.LBB0_471:
	s_andn2_b64 vcc, exec, s[4:5]
	s_cbranch_vccnz .LBB0_500
	v_readlane_b32 s0, v241, 38
	v_readlane_b32 s1, v241, 39
	s_load_dwordx4 s[40:43], s[0:1], 0x70
	v_mov_b32_e32 v2, v0
	v_readlane_b32 s0, v242, 19
	v_and_b32_e32 v3, 63, v2
	v_lshlrev_b32_e32 v4, 2, v3
	s_waitcnt lgkmcnt(0)
	global_load_dword v5, v4, s[40:41]
	global_load_dword v6, v4, s[40:41] offset:256
	global_load_dword v8, v4, s[40:41] offset:512
	global_load_dword v9, v4, s[40:41] offset:768
	v_and_b32_e32 v4, 64, v223
	v_add_u32_e32 v11, 64, v4
	v_xor_b32_e32 v4, 1, v223
	v_cmp_lt_i32_e32 vcc, v4, v11
	v_readlane_b32 s1, v242, 20
	v_readfirstlane_b32 s4, v2
	v_cndmask_b32_e32 v4, v223, v4, vcc
	v_lshlrev_b32_e32 v12, 2, v4
	s_waitcnt vmcnt(0)
	v_mul_f32_e32 v7, v5, v6
	ds_bpermute_b32 v4, v12, v7
	v_mul_f32_e32 v10, v8, v9
	ds_bpermute_b32 v10, v12, v10
	s_waitcnt lgkmcnt(1)
	v_fmac_f32_e32 v4, v5, v6
	v_xor_b32_e32 v5, 2, v223
	v_cmp_lt_i32_e32 vcc, v5, v11
	s_waitcnt lgkmcnt(0)
	v_fmac_f32_e32 v10, v8, v9
	v_cndmask_b32_e32 v5, v223, v5, vcc
	v_lshlrev_b32_e32 v6, 2, v5
	ds_bpermute_b32 v5, v6, v4
	ds_bpermute_b32 v6, v6, v10
	s_waitcnt lgkmcnt(1)
	v_add_f32_e32 v4, v4, v5
	v_xor_b32_e32 v5, 4, v223
	v_cmp_lt_i32_e32 vcc, v5, v11
	s_waitcnt lgkmcnt(0)
	v_add_f32_e32 v6, v10, v6
	v_cndmask_b32_e32 v5, v223, v5, vcc
	v_lshlrev_b32_e32 v7, 2, v5
	ds_bpermute_b32 v5, v7, v4
	ds_bpermute_b32 v7, v7, v6
	s_waitcnt lgkmcnt(1)
	v_add_f32_e32 v4, v4, v5
	v_xor_b32_e32 v5, 8, v223
	v_cmp_lt_i32_e32 vcc, v5, v11
	s_waitcnt lgkmcnt(0)
	v_add_f32_e32 v6, v6, v7
	v_cndmask_b32_e32 v5, v223, v5, vcc
	v_lshlrev_b32_e32 v13, 2, v5
	ds_bpermute_b32 v5, v13, v4
	ds_bpermute_b32 v7, v13, v6
	s_waitcnt lgkmcnt(1)
	v_add_f32_e32 v4, v4, v5
	v_xor_b32_e32 v5, 16, v223
	v_cmp_lt_i32_e32 vcc, v5, v11
	s_waitcnt lgkmcnt(0)
	v_add_f32_e32 v6, v6, v7
	v_cndmask_b32_e32 v5, v223, v5, vcc
	v_lshlrev_b32_e32 v14, 2, v5
	ds_bpermute_b32 v5, v14, v4
	ds_bpermute_b32 v7, v14, v6
	s_waitcnt lgkmcnt(1)
	v_add_f32_e32 v4, v4, v5
	v_xor_b32_e32 v5, 32, v223
	v_cmp_lt_i32_e32 vcc, v5, v11
	s_waitcnt lgkmcnt(0)
	v_add_f32_e32 v6, v6, v7
	v_cndmask_b32_e32 v5, v223, v5, vcc
	v_lshlrev_b32_e32 v67, 2, v5
	ds_bpermute_b32 v5, v67, v4
	ds_bpermute_b32 v7, v67, v6
	s_andn2_b64 vcc, exec, s[0:1]
	s_cbranch_vccnz .LBB0_500
	s_waitcnt lgkmcnt(1)
	v_add_f32_e32 v4, v4, v5
	v_mul_f32_e32 v5, 0x3fb8aa3b, v4
	s_mov_b32 s0, 0x3fb8aa3b
	v_fma_f32 v8, v4, s0, -v5
	v_rndne_f32_e32 v9, v5
	v_fmac_f32_e32 v8, 0x32a5705f, v4
	v_sub_f32_e32 v5, v5, v9
	v_add_f32_e32 v5, v5, v8
	v_cvt_i32_f32_e32 v8, v9
	v_exp_f32_e32 v5, v5
	s_waitcnt lgkmcnt(0)
	v_add_f32_e32 v6, v6, v7
	v_mul_f32_e32 v7, 0x3fb8aa3b, v6
	v_rndne_f32_e32 v9, v7
	v_ldexp_f32 v5, v5, v8
	v_fma_f32 v8, v6, s0, -v7
	v_fmac_f32_e32 v8, 0x32a5705f, v6
	v_sub_f32_e32 v7, v7, v9
	v_add_f32_e32 v7, v7, v8
	v_exp_f32_e32 v7, v7
	v_cvt_i32_f32_e32 v8, v9
	s_mov_b32 s0, 0xc2ce8ed0
	v_cmp_ngt_f32_e32 vcc, s0, v4
	s_mov_b32 s1, 0x42b17218
	s_bfe_u32 s3, s4, 0x20006
	v_cndmask_b32_e32 v5, 0, v5, vcc
	v_cmp_nlt_f32_e32 vcc, s1, v4
	v_and_b32_e32 v10, 31, v2
	s_movk_i32 s7, 0x110
	v_cndmask_b32_e32 v4, v227, v5, vcc
	v_ldexp_f32 v5, v7, v8
	v_cmp_ngt_f32_e32 vcc, s0, v6
	s_ashr_i32 s0, s4, 8
	s_lshl_b32 s11, s0, 6
	v_cndmask_b32_e32 v5, 0, v5, vcc
	v_cmp_nlt_f32_e32 vcc, s1, v6
	v_lshlrev_b32_e32 v6, 3, v2
	v_lshlrev_b32_e32 v7, 4, v2
	v_cndmask_b32_e32 v5, v227, v5, vcc
	v_sub_f32_e32 v4, v4, v5
	v_add_f32_e32 v190, 0x3e4ccccd, v4
	v_lshrrev_b32_e32 v5, 5, v3
	s_add_u32 s28, s74, 0x7e00800
	v_and_b32_e32 v4, 56, v6
	v_and_b32_e32 v7, 0x60, v7
	v_and_b32_e32 v6, 8, v6
	v_lshlrev_b32_e32 v192, 3, v5
	s_addc_u32 s29, s75, 0
	v_add3_u32 v193, 0, v7, v6
	v_mad_u32_u24 v6, v10, s7, 0
	s_lshl_b32 s1, s0, 7
	v_lshlrev_b32_e32 v184, 4, v5
	v_lshlrev_b32_e32 v5, 7, v10
	v_add3_u32 v214, v6, s1, v184
	v_sub_u32_e32 v5, v6, v5
	s_lshl_b32 s1, s3, 14
	v_add_u32_e32 v215, v5, v184
	s_add_i32 s1, s1, 0
	v_add_u32_e32 v5, 0x200, v2
	v_lshl_add_u32 v216, v3, 2, s1
	v_ashrrev_i32_e32 v3, 31, v2
	v_ashrrev_i32_e32 v8, 31, v5
	v_lshrrev_b32_e32 v3, 28, v3
	v_lshrrev_b32_e32 v8, 28, v8
	v_add_u32_e32 v3, v2, v3
	v_add_u32_e32 v8, v5, v8
	v_ashrrev_i32_e32 v217, 4, v3
	v_and_b32_e32 v3, -16, v3
	v_ashrrev_i32_e32 v218, 4, v8
	v_and_b32_e32 v8, -16, v8
	s_mov_b32 s54, s6
	s_cmp_eq_u32 s0, 1
	v_sub_u32_e32 v3, v2, v3
	v_sub_u32_e32 v11, v5, v8
	v_ashrrev_i32_e32 v2, 3, v2
	s_movk_i32 s6, 0x2200
	v_ashrrev_i32_e32 v5, 3, v5
	s_cselect_b64 s[0:1], -1, 0
	s_cmpk_lt_u32 s4, 0x100
	v_lshlrev_b32_e32 v6, 3, v3
	v_lshlrev_b32_e32 v8, 3, v11
	v_mad_i64_i32 v[196:197], s[4:5], v2, s6, 0
	v_mad_i64_i32 v[198:199], s[4:5], v5, s6, 0
	v_mul_lo_u32 v219, v217, s7
	v_mul_lo_u32 v229, v218, s7
	v_ashrrev_i32_e32 v7, 31, v6
	v_ashrrev_i32_e32 v9, 31, v8
	v_add_u32_e32 v12, 0, v219
	v_lshlrev_b32_e32 v228, 4, v3
	v_add_u32_e32 v3, 0, v229
	v_lshlrev_b32_e32 v230, 4, v11
	s_movk_i32 s4, 0x90
	s_cselect_b64 s[20:21], -1, 0
	v_lshl_add_u64 v[194:195], s[42:43], 0, v[184:185]
	v_mul_lo_u32 v231, v2, s4
	v_mul_lo_u32 v232, v5, s4
	v_mov_b32_e32 v191, v190
	v_lshl_or_b32 v233, s3, 5, v10
	v_lshlrev_b64 v[200:201], 1, v[6:7]
	v_lshlrev_b64 v[202:203], 1, v[8:9]
	v_lshlrev_b32_e32 v204, 1, v4
	v_add_u32_e32 v234, v12, v228
	v_add_u32_e32 v235, v3, v230
	v_readlane_b32 s44, v241, 38
	v_readlane_b32 s45, v241, 39
	s_nop 0
	s_load_dwordx4 s[44:47], s[44:45], 0x60
	v_and_b32_e32 v40, 63, v0
	v_lshlrev_b32_e32 v40, 2, v40
	s_waitcnt lgkmcnt(0)
	global_load_dword v41, v40, s[44:45]
	global_load_dword v42, v40, s[46:47]
	s_waitcnt vmcnt(0)
	v_and_b32_e32 v41, 0x7fffffff, v41
	v_and_b32_e32 v42, 0x7fffffff, v42
	v_xor_b32_e32 v43, 1, v223
	v_lshlrev_b32_e32 v43, 2, v43
	ds_bpermute_b32 v44, v43, v41
	ds_bpermute_b32 v45, v43, v42
	s_waitcnt lgkmcnt(0)
	v_max_f32_e32 v41, v41, v44
	v_max_f32_e32 v42, v42, v45
	v_xor_b32_e32 v43, 2, v223
	v_lshlrev_b32_e32 v43, 2, v43
	ds_bpermute_b32 v44, v43, v41
	ds_bpermute_b32 v45, v43, v42
	s_waitcnt lgkmcnt(0)
	v_max_f32_e32 v41, v41, v44
	v_max_f32_e32 v42, v42, v45
	v_xor_b32_e32 v43, 4, v223
	v_lshlrev_b32_e32 v43, 2, v43
	ds_bpermute_b32 v44, v43, v41
	ds_bpermute_b32 v45, v43, v42
	s_waitcnt lgkmcnt(0)
	v_max_f32_e32 v41, v41, v44
	v_max_f32_e32 v42, v42, v45
	v_xor_b32_e32 v43, 8, v223
	v_lshlrev_b32_e32 v43, 2, v43
	ds_bpermute_b32 v44, v43, v41
	ds_bpermute_b32 v45, v43, v42
	s_waitcnt lgkmcnt(0)
	v_max_f32_e32 v41, v41, v44
	v_max_f32_e32 v42, v42, v45
	v_xor_b32_e32 v43, 16, v223
	v_lshlrev_b32_e32 v43, 2, v43
	ds_bpermute_b32 v44, v43, v41
	ds_bpermute_b32 v45, v43, v42
	s_waitcnt lgkmcnt(0)
	v_max_f32_e32 v41, v41, v44
	v_max_f32_e32 v42, v42, v45
	v_xor_b32_e32 v43, 32, v223
	v_lshlrev_b32_e32 v43, 2, v43
	ds_bpermute_b32 v44, v43, v41
	ds_bpermute_b32 v45, v43, v42
	s_waitcnt lgkmcnt(0)
	v_max_f32_e32 v41, v41, v44
	v_max_f32_e32 v42, v42, v45
	v_mul_f32_e32 v41, v41, v42
	v_cmp_gt_f32_e32 vcc, 4.0, v41
	s_nop 3
	s_cmp_lg_u64 vcc, 0
	s_cselect_b32 s100, 1, 0
	s_mov_b32 s30, s2
	s_branch .LBB0_475

.LBB0_484:
	s_lshl_b32 s3, s5, 7
	s_and_b32 s23, s3, 0x380
	v_ashrrev_i32_e32 v207, 31, v206
	s_ashr_i32 s5, s4, 31
	s_add_i32 s24, s23, s11
	v_lshlrev_b64 v[4:5], 12, v[206:207]
	s_lshl_b64 s[4:5], s[4:5], 10
	v_lshl_add_u64 v[4:5], s[80:81], 0, v[4:5]
	s_ashr_i32 s25, s24, 31
	s_or_b32 s3, s4, s23
	v_lshl_add_u64 v[4:5], s[24:25], 1, v[4:5]
	v_lshlrev_b32_e32 v184, 1, v192
	s_mul_i32 s24, s3, 0x2200
	s_mul_hi_u32 s3, s3, 0x2200
	s_mul_i32 s4, s5, 0x2200
	s_or_b32 s17, s10, 4
	v_lshl_add_u64 v[4:5], v[4:5], 0, v[184:185]
	s_add_i32 s3, s3, s4
	s_lshl_b32 s4, s23, 1
	global_load_dwordx4 v[160:163], v[4:5], off
	global_load_dwordx4 v[156:159], v[4:5], off offset:32
	global_load_dwordx4 v[152:155], v[4:5], off offset:64
	global_load_dwordx4 v[148:151], v[4:5], off offset:96
	s_add_u32 s4, s28, s4
	v_add_u32_e32 v4, v2, v217
	s_addc_u32 s5, s29, 0
	v_readlane_b32 s36, v241, 45
	v_ashrrev_i32_e32 v5, 31, v4
	v_add_u32_e32 v2, v2, v218
	v_readlane_b32 s37, v241, 46
	s_add_u32 s24, s36, s24
	v_lshlrev_b64 v[4:5], 12, v[4:5]
	v_ashrrev_i32_e32 v3, 31, v2
	s_addc_u32 s25, s37, s3
	v_lshl_add_u64 v[4:5], s[4:5], 0, v[4:5]
	v_lshlrev_b64 v[2:3], 12, v[2:3]
	s_lshl_b32 s3, s26, 1
	v_lshl_add_u64 v[4:5], v[4:5], 0, v[200:201]
	v_lshl_add_u64 v[2:3], s[4:5], 0, v[2:3]
	s_add_u32 s26, s24, s3
	global_load_dwordx4 v[4:7], v[4:5], off
	v_lshl_add_u64 v[2:3], v[2:3], 0, v[202:203]
	s_addc_u32 s27, s25, 0
	v_mov_b32_e32 v205, v185
	global_load_dwordx4 v[8:11], v[2:3], off
	v_lshl_add_u64 v[2:3], s[26:27], 0, v[204:205]
	v_lshl_add_u64 v[12:13], v[2:3], 0, v[196:197]
	global_load_dwordx4 v[12:15], v[12:13], off
	v_lshl_add_u64 v[2:3], v[2:3], 0, v[198:199]
	global_load_dwordx4 v[16:19], v[2:3], off
	s_or_b32 s3, s16, 64
	s_add_i32 s34, s31, 0x4040
	s_and_b64 s[26:27], s[6:7], exec
	s_cselect_b32 s3, s3, s34
	v_add_u32_e32 v2, s3, v217
	v_ashrrev_i32_e32 v3, 31, v2
	v_add_u32_e32 v20, v193, v231
	v_lshlrev_b64 v[2:3], 12, v[2:3]
	v_add_u32_e32 v237, 0x8800, v20
	v_lshl_add_u64 v[2:3], s[4:5], 0, v[2:3]
	v_lshl_add_u64 v[2:3], v[2:3], 0, v[200:201]
	v_add_u32_e32 v21, v193, v232
	v_add_u32_e32 v236, 0x8800, v21
	v_lshl_add_u64 v[208:209], s[24:25], 0, v[204:205]
	v_readlane_b32 s36, v242, 63
	v_readlane_b32 s37, v241, 0
	v_readlane_b32 s38, v241, 1
	v_readlane_b32 s39, v241, 2
	v_readlane_b32 s40, v241, 3
	v_readlane_b32 s41, v241, 4
	v_readlane_b32 s42, v241, 5
	v_readlane_b32 s43, v241, 6
	v_readlane_b32 s44, v241, 7
	v_readlane_b32 s45, v241, 8
	v_readlane_b32 s46, v241, 9
	v_readlane_b32 s47, v241, 10
	v_readlane_b32 s48, v241, 11
	v_readlane_b32 s49, v241, 12
	v_readlane_b32 s50, v241, 13
	v_readlane_b32 s51, v241, 14
	v_mov_b64_e32 v[34:35], s[36:37]
	v_mov_b64_e32 v[36:37], s[38:39]
	v_mov_b64_e32 v[38:39], s[40:41]
	v_mov_b64_e32 v[40:41], s[42:43]
	v_mov_b64_e32 v[42:43], s[44:45]
	v_mov_b64_e32 v[44:45], s[46:47]
	v_mov_b64_e32 v[46:47], s[48:49]
	v_mov_b64_e32 v[48:49], s[50:51]
	v_mov_b64_e32 v[100:101], s[70:71]
	v_mov_b64_e32 v[98:99], s[68:69]
	v_lshl_add_u64 v[210:211], s[4:5], 0, v[200:201]
	v_lshl_add_u64 v[212:213], s[4:5], 0, v[202:203]
	v_readlane_b32 s48, v241, 29
	s_waitcnt vmcnt(3)
	ds_write_b128 v234, v[4:7]
	s_waitcnt vmcnt(2)
	ds_write_b128 v235, v[8:11]
	v_add_u32_e32 v6, s3, v218
	s_lshl_b32 s3, s22, 1
	v_ashrrev_i32_e32 v7, 31, v6
	s_add_u32 s26, s24, s3
	v_lshlrev_b64 v[6:7], 12, v[6:7]
	s_addc_u32 s27, s25, 0
	s_waitcnt vmcnt(1)
	ds_write2_b64 v237, v[12:13], v[14:15] offset1:2
	v_lshl_add_u64 v[6:7], s[4:5], 0, v[6:7]
	v_lshl_add_u64 v[14:15], s[26:27], 0, v[204:205]
	global_load_dwordx4 v[2:5], v[2:3], off
	v_lshl_add_u64 v[6:7], v[6:7], 0, v[202:203]
	v_lshl_add_u64 v[10:11], v[14:15], 0, v[196:197]
	global_load_dwordx4 v[6:9], v[6:7], off
	v_lshl_add_u64 v[14:15], v[14:15], 0, v[198:199]
	global_load_dwordx4 v[10:13], v[10:11], off
	s_waitcnt vmcnt(3)
	ds_write2_b64 v236, v[16:17], v[18:19] offset1:2
	global_load_dwordx4 v[14:17], v[14:15], off
	s_add_i32 s22, s31, 0x3000
	s_sub_i32 s3, 0x42, s10
	s_and_b64 s[6:7], s[6:7], exec
	s_cselect_b32 s3, 2, s3
	s_lshl_b32 s7, s3, 6
	s_or_b32 s6, s16, 0x80
	s_add_i32 s24, s22, s7
	s_waitcnt lgkmcnt(0)
	s_barrier
	s_cmp_lt_u32 s3, 64
	s_cselect_b32 s6, s6, s24
	s_cselect_b32 s3, 0x80, s7
	s_lshl_b32 s78, s3, 1
	s_waitcnt vmcnt(3)
	ds_write_b128 v234, v[2:5] offset:17408
	s_waitcnt vmcnt(2)
	ds_write_b128 v235, v[6:9] offset:17408
	v_add_u32_e32 v2, 0xd000, v20
	s_waitcnt vmcnt(1)
	ds_write2_b64 v2, v[10:11], v[12:13] offset1:2
	v_add_u32_e32 v2, 0xd000, v21
	s_waitcnt vmcnt(0)
	ds_write2_b64 v2, v[14:15], v[16:17] offset1:2
	v_add_u32_e32 v2, s6, v217
	v_ashrrev_i32_e32 v3, 31, v2
	v_lshlrev_b64 v[2:3], 12, v[2:3]
	v_lshl_add_u64 v[2:3], s[4:5], 0, v[2:3]
	v_lshl_add_u64 v[2:3], v[2:3], 0, v[200:201]
	global_load_dwordx4 v[164:167], v[2:3], off
	v_add_u32_e32 v2, s6, v218
	v_ashrrev_i32_e32 v3, 31, v2
	v_lshlrev_b64 v[2:3], 12, v[2:3]
	v_lshl_add_u64 v[2:3], s[4:5], 0, v[2:3]
	v_lshl_add_u64 v[2:3], v[2:3], 0, v[202:203]
	global_load_dwordx4 v[168:171], v[2:3], off
	v_lshl_add_u64 v[2:3], v[208:209], 0, s[78:79]
	v_lshl_add_u64 v[4:5], v[2:3], 0, v[196:197]
	v_lshl_add_u64 v[2:3], v[2:3], 0, v[198:199]
	global_load_dwordx4 v[176:179], v[4:5], off
	global_load_dwordx4 v[172:175], v[2:3], off
	ds_read_b128 v[50:53], v214 offset:8704
	ds_read_b128 v[18:21], v214
	ds_read_b128 v[54:57], v214 offset:32
	s_waitcnt lgkmcnt(1)
	v_mfma_f32_32x32x16_bf16 v[2:17], v[18:21], v[160:163], v[34:49]
	s_mov_b32 s5, 0
	s_sub_i32 s6, 0, s10
	v_mfma_f32_32x32x16_bf16 v[18:33], v[50:53], v[160:163], v[34:49]
	s_nop 6
	ds_read_b128 v[34:37], v214 offset:8736
	s_waitcnt lgkmcnt(1)
	v_mfma_f32_32x32x16_bf16 v[2:17], v[54:57], v[156:159], v[2:17]
	s_waitcnt lgkmcnt(0)
	v_mfma_f32_32x32x16_bf16 v[18:33], v[34:37], v[156:159], v[18:33]
	ds_read_b128 v[34:37], v214 offset:64
	ds_read_b128 v[38:41], v214 offset:8768
	s_waitcnt lgkmcnt(1)
	v_mfma_f32_32x32x16_bf16 v[2:17], v[34:37], v[152:155], v[2:17]
	s_waitcnt lgkmcnt(0)
	v_mfma_f32_32x32x16_bf16 v[18:33], v[38:41], v[152:155], v[18:33]
	ds_read_b128 v[34:37], v214 offset:96
	ds_read_b128 v[38:41], v214 offset:8800
	s_waitcnt lgkmcnt(1)
	v_mfma_f32_32x32x16_bf16 v[2:17], v[34:37], v[148:151], v[2:17]
	s_waitcnt lgkmcnt(0)
	v_mfma_f32_32x32x16_bf16 v[18:33], v[38:41], v[148:151], v[18:33]
	s_nop 9
	v_max_f32_e32 v34, v3, v3
	v_max_f32_e32 v35, v2, v2
	v_max_f32_e32 v34, v35, v34
	v_max3_f32 v35, v5, v6, v7
	v_max3_f32 v34, v34, v4, v8
	v_max3_f32 v35, v35, v10, v11
	v_max3_f32 v34, v34, v9, v12
	v_max3_f32 v36, v18, v19, v20
	v_max3_f32 v37, v21, v22, v23
	v_max3_f32 v36, v36, v24, v25
	v_max3_f32 v37, v37, v26, v27
	v_max3_f32 v35, v35, v14, v15
	v_max3_f32 v36, v36, v28, v29
	v_max3_f32 v34, v34, v13, v16
	v_max3_f32 v37, v37, v30, v31
	v_max3_f32 v36, v36, v32, v33
	v_max3_f32 v34, v34, v17, v35
	v_max3_f32 v34, v34, v36, v37
	ds_bpermute_b32 v35, v67, v34
	s_waitcnt lgkmcnt(0)
	v_max_f32_e32 v35, v35, v35
	v_max_f32_e32 v205, v34, v35
	v_sub_f32_e32 v2, v2, v205
	v_sub_f32_e32 v3, v3, v205
	v_sub_f32_e32 v4, v4, v205
	v_sub_f32_e32 v5, v5, v205
	v_exp_f32_e32 v2, v2
	v_exp_f32_e32 v3, v3
	v_exp_f32_e32 v4, v4
	v_exp_f32_e32 v5, v5
	v_sub_f32_e32 v6, v6, v205
	v_sub_f32_e32 v7, v7, v205
	v_sub_f32_e32 v8, v8, v205
	v_sub_f32_e32 v9, v9, v205
	v_exp_f32_e32 v6, v6
	v_exp_f32_e32 v7, v7
	v_exp_f32_e32 v8, v8
	v_exp_f32_e32 v9, v9
	v_cvt_pk_bf16_f32 v68, v2, v3
	v_cvt_pk_bf16_f32 v69, v4, v5
	ds_read_b128 v[2:5], v215 offset:34816
	ds_read_b128 v[72:75], v215 offset:34848
	v_cvt_pk_bf16_f32 v70, v6, v7
	v_cvt_pk_bf16_f32 v71, v8, v9
	v_sub_f32_e32 v10, v10, v205
	v_sub_f32_e32 v11, v11, v205
	s_waitcnt lgkmcnt(1)
	v_mfma_f32_32x32x16_bf16 v[50:65], v[2:5], v[68:71], 0
	ds_read_b128 v[2:5], v215 offset:39424
	v_sub_f32_e32 v12, v12, v205
	v_sub_f32_e32 v13, v13, v205
	v_sub_f32_e32 v14, v14, v205
	v_sub_f32_e32 v15, v15, v205
	v_sub_f32_e32 v16, v16, v205
	v_sub_f32_e32 v17, v17, v205
	v_exp_f32_e32 v10, v10
	v_exp_f32_e32 v11, v11
	v_exp_f32_e32 v12, v12
	v_exp_f32_e32 v13, v13
	v_exp_f32_e32 v14, v14
	v_exp_f32_e32 v15, v15
	v_exp_f32_e32 v16, v16
	v_exp_f32_e32 v17, v17
	v_cvt_pk_bf16_f32 v94, v10, v11
	v_cvt_pk_bf16_f32 v95, v12, v13
	v_cvt_pk_bf16_f32 v96, v14, v15
	v_cvt_pk_bf16_f32 v97, v16, v17
	v_sub_f32_e32 v18, v18, v205
	v_sub_f32_e32 v19, v19, v205
	s_waitcnt lgkmcnt(1)
	v_mfma_f32_32x32x16_bf16 v[50:65], v[72:75], v[94:97], v[50:65]
	ds_read_b128 v[72:75], v215 offset:39456
	v_sub_f32_e32 v20, v20, v205
	v_sub_f32_e32 v21, v21, v205
	v_sub_f32_e32 v22, v22, v205
	v_sub_f32_e32 v23, v23, v205
	v_sub_f32_e32 v24, v24, v205
	v_sub_f32_e32 v25, v25, v205
	s_waitcnt lgkmcnt(1)
	v_mfma_f32_32x32x16_bf16 v[34:49], v[2:5], v[68:71], 0
	ds_read_b128 v[2:5], v215 offset:44032
	v_sub_f32_e32 v26, v26, v205
	v_sub_f32_e32 v27, v27, v205
	v_sub_f32_e32 v28, v28, v205
	v_sub_f32_e32 v29, v29, v205
	v_sub_f32_e32 v30, v30, v205
	v_sub_f32_e32 v31, v31, v205
	v_sub_f32_e32 v32, v32, v205
	v_sub_f32_e32 v33, v33, v205
	v_exp_f32_e32 v18, v18
	v_exp_f32_e32 v19, v19
	v_exp_f32_e32 v20, v20
	v_exp_f32_e32 v21, v21
	v_exp_f32_e32 v22, v22
	v_exp_f32_e32 v23, v23
	v_exp_f32_e32 v24, v24
	v_exp_f32_e32 v25, v25
	v_exp_f32_e32 v26, v26
	v_exp_f32_e32 v27, v27
	v_exp_f32_e32 v28, v28
	v_exp_f32_e32 v29, v29
	v_exp_f32_e32 v30, v30
	v_exp_f32_e32 v31, v31
	v_exp_f32_e32 v32, v32
	v_exp_f32_e32 v33, v33
	s_waitcnt lgkmcnt(1)
	v_mfma_f32_32x32x16_bf16 v[34:49], v[72:75], v[94:97], v[34:49]
	ds_read_b128 v[72:75], v215 offset:44064
	v_cvt_pk_bf16_f32 v90, v18, v19
	v_cvt_pk_bf16_f32 v91, v20, v21
	v_cvt_pk_bf16_f32 v92, v22, v23
	v_cvt_pk_bf16_f32 v93, v24, v25
	v_cvt_pk_bf16_f32 v86, v26, v27
	v_cvt_pk_bf16_f32 v87, v28, v29
	v_cvt_pk_bf16_f32 v88, v30, v31
	v_cvt_pk_bf16_f32 v89, v32, v33
	s_waitcnt lgkmcnt(1)
	v_mfma_f32_32x32x16_bf16 v[18:33], v[2:5], v[68:71], 0
	ds_read_b128 v[2:5], v215 offset:48640
	v_xor_b32_e32 v84, 0x80000000, v205
	v_mov_b32_e32 v85, v84
	s_waitcnt lgkmcnt(1)
	v_mfma_f32_32x32x16_bf16 v[18:33], v[72:75], v[94:97], v[18:33]
	ds_read_b128 v[72:75], v215 offset:48672
	s_waitcnt lgkmcnt(1)
	v_mfma_f32_32x32x16_bf16 v[2:17], v[2:5], v[68:71], 0
	s_waitcnt lgkmcnt(0)
	v_mfma_f32_32x32x16_bf16 v[2:17], v[72:75], v[94:97], v[2:17]
	ds_read_b128 v[72:75], v215 offset:34880
	s_waitcnt lgkmcnt(0)
	v_mfma_f32_32x32x16_bf16 v[50:65], v[72:75], v[90:93], v[50:65]
	ds_read_b128 v[72:75], v215 offset:39488
	s_waitcnt lgkmcnt(0)
	v_mfma_f32_32x32x16_bf16 v[34:49], v[72:75], v[90:93], v[34:49]
	ds_read_b128 v[72:75], v215 offset:44096
	s_waitcnt lgkmcnt(0)
	v_mfma_f32_32x32x16_bf16 v[18:33], v[72:75], v[90:93], v[18:33]
	ds_read_b128 v[72:75], v215 offset:48704
	s_waitcnt lgkmcnt(0)
	v_mfma_f32_32x32x16_bf16 v[2:17], v[72:75], v[90:93], v[2:17]
	ds_read_b128 v[72:75], v215 offset:34912
	s_waitcnt lgkmcnt(0)
	v_mfma_f32_32x32x16_bf16 v[50:65], v[72:75], v[86:89], v[50:65]
	ds_read_b128 v[72:75], v215 offset:39520
	s_waitcnt lgkmcnt(0)
	v_mfma_f32_32x32x16_bf16 v[34:49], v[72:75], v[86:89], v[34:49]
	ds_read_b128 v[72:75], v215 offset:44128
	s_waitcnt lgkmcnt(0)
	v_mfma_f32_32x32x16_bf16 v[18:33], v[72:75], v[86:89], v[18:33]
	ds_read_b128 v[72:75], v215 offset:48736
	s_waitcnt lgkmcnt(0)
	s_barrier
	v_mfma_f32_32x32x16_bf16 v[2:17], v[72:75], v[86:89], v[2:17]
	v_mfma_f32_32x32x16_bf16 v[68:83], v[98:101], v[68:71], 0
	v_mfma_f32_32x32x16_bf16 v[68:83], v[98:101], v[94:97], v[68:83]
	v_mov_b32_e32 v94, v84
	v_mov_b32_e32 v95, v84
	v_mov_b32_e32 v96, v84
	v_mov_b32_e32 v97, v84
	v_mfma_f32_32x32x16_bf16 v[68:83], v[98:101], v[90:93], v[68:83]
	v_mov_b32_e32 v90, v84
	v_mov_b32_e32 v91, v84
	v_mov_b32_e32 v92, v84
	v_mov_b32_e32 v93, v84
	v_mfma_f32_32x32x16_bf16 v[68:83], v[98:101], v[86:89], v[68:83]
	v_mov_b32_e32 v86, v84
	v_mov_b32_e32 v87, v84
	v_mov_b32_e32 v88, v84
	v_mov_b32_e32 v89, v84
	v_mov_b32_e32 v98, v84
	v_mov_b32_e32 v99, v84
	s_cmp_lg_u32 s100, 0
	s_cbranch_scc1 .Lattn_af_loop

.Lattn_a_exit:
	s_waitcnt vmcnt(0)
	v_mov_b64_e32 v[100:101], v[84:85]
	v_mov_b64_e32 v[102:103], v[86:87]
	v_mov_b64_e32 v[104:105], v[88:89]
	v_mov_b64_e32 v[106:107], v[90:91]
	v_mov_b64_e32 v[108:109], v[92:93]
	v_mov_b64_e32 v[110:111], v[94:95]
	v_mov_b64_e32 v[112:113], v[96:97]
	v_mov_b64_e32 v[114:115], v[98:99]
	s_branch .LBB0_491

.Lattn_af_loop:
	s_add_i32 s5, s5, 1
	s_and_b32 s24, s5, 1
	s_mul_i32 s3, s24, 0x4400
	s_mulk_i32 s24, 0x4800
	v_add_u32_e32 v238, s3, v214
	v_add_u32_e32 v239, s24, v215
	ds_read_b128 v[100:103], v238
	ds_read_b128 v[104:107], v238 offset:8704
	ds_read_b128 v[108:111], v238 offset:32
	ds_read_b128 v[112:115], v238 offset:8736
	ds_read_b128 v[244:247], v238 offset:64
	ds_read_b128 v[248:251], v238 offset:8768
	s_add_i32 s3, s5, 1
	s_and_b32 s4, s3, 1
	s_mul_i32 s7, s4, 0x4400
	s_mulk_i32 s4, 0x4800
	v_add3_u32 v240, s7, v219, v228
	v_add3_u32 v243, s7, v229, v230
	s_waitcnt vmcnt(0)
	ds_write_b128 v240, v[164:167]
	ds_write_b128 v243, v[168:171]
	v_add_u32_e32 v240, s4, v193
	v_add_u32_e32 v243, v240, v231
	v_add_u32_e32 v240, v240, v232
	v_add_u32_e32 v243, 0x8800, v243
	v_add_u32_e32 v240, 0x8800, v240
	ds_write2_b64 v243, v[176:177], v[178:179] offset1:2
	ds_write2_b64 v240, v[172:173], v[174:175] offset1:2
	s_waitcnt lgkmcnt(9)
	v_mfma_f32_32x32x16_bf16 v[116:131], v[100:103], v[160:163], v[84:99]
	ds_read_b128 v[100:103], v238 offset:96
	s_add_i32 s24, s5, 2
	s_add_i32 s3, s6, s5
	s_addk_i32 s3, 0x42
	s_cmp_lt_u32 s24, s10
	s_waitcnt lgkmcnt(9)
	v_mfma_f32_32x32x16_bf16 v[132:147], v[104:107], v[160:163], v[84:99]
	ds_read_b128 v[104:107], v238 offset:8800
	s_cselect_b32 s3, s24, s3
	s_lshl_b32 s78, s3, 6
	s_add_i32 s24, s78, s22
	s_or_b32 s25, s78, s16
	s_waitcnt lgkmcnt(9)
	v_mfma_f32_32x32x16_bf16 v[116:131], v[108:111], v[156:159], v[116:131]
	ds_read_b128 v[108:111], v239 offset:34816
	s_cmp_lt_u32 s3, 64
	s_cselect_b32 s3, s25, s24
	v_add_u32_e32 v252, s3, v217
	v_add_u32_e32 v254, s3, v218
	s_waitcnt lgkmcnt(9)
	v_mfma_f32_32x32x16_bf16 v[132:147], v[112:115], v[156:159], v[132:147]
	ds_read_b128 v[112:115], v239 offset:39424
	v_ashrrev_i32_e32 v253, 31, v252
	v_ashrrev_i32_e32 v255, 31, v254
	v_lshlrev_b64 v[252:253], 12, v[252:253]
	v_lshlrev_b64 v[254:255], 12, v[254:255]
	s_waitcnt lgkmcnt(9)
	v_mfma_f32_32x32x16_bf16 v[116:131], v[244:247], v[152:155], v[116:131]
	ds_read_b128 v[244:247], v239 offset:44032
	v_lshl_add_u64 v[252:253], v[210:211], 0, v[252:253]
	v_lshl_add_u64 v[254:255], v[212:213], 0, v[254:255]
	global_load_dwordx4 v[164:167], v[252:253], off
	global_load_dwordx4 v[168:171], v[254:255], off
	s_waitcnt lgkmcnt(9)
	v_mfma_f32_32x32x16_bf16 v[132:147], v[248:251], v[152:155], v[132:147]
	ds_read_b128 v[248:251], v239 offset:48640
	v_lshl_add_u64 v[252:253], s[78:79], 1, v[208:209]
	v_lshl_add_u64 v[254:255], v[252:253], 0, v[196:197]
	v_lshl_add_u64 v[252:253], v[252:253], 0, v[198:199]
	global_load_dwordx4 v[176:179], v[254:255], off
	s_waitcnt lgkmcnt(5)
	v_mfma_f32_32x32x16_bf16 v[116:131], v[100:103], v[148:151], v[116:131]
	ds_read_b128 v[100:103], v239 offset:34848
	global_load_dwordx4 v[172:175], v[252:253], off
	s_waitcnt lgkmcnt(5)
	v_mfma_f32_32x32x16_bf16 v[132:147], v[104:107], v[148:151], v[132:147]
	ds_read_b128 v[104:107], v239 offset:39456
	s_nop 6
	v_exp_f32_e32 v116, v116
	v_exp_f32_e32 v117, v117
	v_exp_f32_e32 v118, v118
	v_exp_f32_e32 v119, v119
	v_exp_f32_e32 v120, v120
	v_exp_f32_e32 v121, v121
	v_exp_f32_e32 v122, v122
	v_exp_f32_e32 v123, v123
	v_cvt_pk_bf16_f32 v116, v116, v117
	v_cvt_pk_bf16_f32 v117, v118, v119
	v_cvt_pk_bf16_f32 v118, v120, v121
	v_cvt_pk_bf16_f32 v119, v122, v123
	v_mov_b64_e32 v[252:253], s[68:69]
	v_mov_b64_e32 v[254:255], s[70:71]
	s_waitcnt lgkmcnt(5)
	v_mfma_f32_32x32x16_bf16 v[50:65], v[108:111], v[116:119], v[50:65]
	v_exp_f32_e32 v124, v124
	v_exp_f32_e32 v125, v125
	ds_read_b128 v[108:111], v239 offset:44064
	s_waitcnt lgkmcnt(5)
	v_mfma_f32_32x32x16_bf16 v[34:49], v[112:115], v[116:119], v[34:49]
	v_exp_f32_e32 v126, v126
	v_exp_f32_e32 v127, v127
	ds_read_b128 v[112:115], v239 offset:48672
	s_waitcnt lgkmcnt(5)
	v_mfma_f32_32x32x16_bf16 v[18:33], v[244:247], v[116:119], v[18:33]
	v_exp_f32_e32 v128, v128
	v_exp_f32_e32 v129, v129
	ds_read_b128 v[244:247], v239 offset:34880
	s_waitcnt lgkmcnt(5)
	v_mfma_f32_32x32x16_bf16 v[2:17], v[248:251], v[116:119], v[2:17]
	v_exp_f32_e32 v130, v130
	v_exp_f32_e32 v131, v131
	v_cvt_pk_bf16_f32 v120, v124, v125
	v_cvt_pk_bf16_f32 v121, v126, v127
	v_cvt_pk_bf16_f32 v122, v128, v129
	v_cvt_pk_bf16_f32 v123, v130, v131
	ds_read_b128 v[248:251], v239 offset:39488
	s_waitcnt lgkmcnt(5)
	v_mfma_f32_32x32x16_bf16 v[50:65], v[100:103], v[120:123], v[50:65]
	v_exp_f32_e32 v132, v132
	v_exp_f32_e32 v133, v133
	ds_read_b128 v[100:103], v239 offset:44096
	s_waitcnt lgkmcnt(5)
	v_mfma_f32_32x32x16_bf16 v[34:49], v[104:107], v[120:123], v[34:49]
	v_exp_f32_e32 v134, v134
	v_exp_f32_e32 v135, v135
	ds_read_b128 v[104:107], v239 offset:48704
	s_waitcnt lgkmcnt(5)
	v_mfma_f32_32x32x16_bf16 v[18:33], v[108:111], v[120:123], v[18:33]
	v_exp_f32_e32 v136, v136
	v_exp_f32_e32 v137, v137
	ds_read_b128 v[108:111], v239 offset:34912
	s_waitcnt lgkmcnt(5)
	v_mfma_f32_32x32x16_bf16 v[2:17], v[112:115], v[120:123], v[2:17]
	v_exp_f32_e32 v138, v138
	v_exp_f32_e32 v139, v139
	v_cvt_pk_bf16_f32 v124, v132, v133
	v_cvt_pk_bf16_f32 v125, v134, v135
	v_cvt_pk_bf16_f32 v126, v136, v137
	v_cvt_pk_bf16_f32 v127, v138, v139
	ds_read_b128 v[112:115], v239 offset:39520
	s_waitcnt lgkmcnt(5)
	v_mfma_f32_32x32x16_bf16 v[50:65], v[244:247], v[124:127], v[50:65]
	v_exp_f32_e32 v140, v140
	v_exp_f32_e32 v141, v141
	ds_read_b128 v[244:247], v239 offset:44128
	s_waitcnt lgkmcnt(5)
	v_mfma_f32_32x32x16_bf16 v[34:49], v[248:251], v[124:127], v[34:49]
	v_exp_f32_e32 v142, v142
	v_exp_f32_e32 v143, v143
	ds_read_b128 v[248:251], v239 offset:48736
	s_waitcnt lgkmcnt(5)
	v_mfma_f32_32x32x16_bf16 v[18:33], v[100:103], v[124:127], v[18:33]
	v_exp_f32_e32 v144, v144
	v_exp_f32_e32 v145, v145
	s_waitcnt lgkmcnt(4)
	v_mfma_f32_32x32x16_bf16 v[2:17], v[104:107], v[124:127], v[2:17]
	v_exp_f32_e32 v146, v146
	v_exp_f32_e32 v147, v147
	v_cvt_pk_bf16_f32 v128, v140, v141
	v_cvt_pk_bf16_f32 v129, v142, v143
	v_cvt_pk_bf16_f32 v130, v144, v145
	v_cvt_pk_bf16_f32 v131, v146, v147
	s_nop 0
	s_waitcnt lgkmcnt(3)
	v_mfma_f32_32x32x16_bf16 v[50:65], v[108:111], v[128:131], v[50:65]
	s_waitcnt lgkmcnt(2)
	v_mfma_f32_32x32x16_bf16 v[34:49], v[112:115], v[128:131], v[34:49]
	s_waitcnt lgkmcnt(1)
	v_mfma_f32_32x32x16_bf16 v[18:33], v[244:247], v[128:131], v[18:33]
	s_waitcnt lgkmcnt(0)
	s_barrier
	v_mfma_f32_32x32x16_bf16 v[2:17], v[248:251], v[128:131], v[2:17]
	v_mfma_f32_32x32x16_bf16 v[68:83], v[252:255], v[116:119], v[68:83]
	v_mfma_f32_32x32x16_bf16 v[68:83], v[252:255], v[120:123], v[68:83]
	v_mfma_f32_32x32x16_bf16 v[68:83], v[252:255], v[124:127], v[68:83]
	v_mfma_f32_32x32x16_bf16 v[68:83], v[252:255], v[128:131], v[68:83]
	s_add_i32 s3, s6, s5
	s_cmp_eq_u32 s3, 2
	s_cbranch_scc0 .Lattn_af_loop
	s_branch .Lattn_a_exit

	.amdhsa_kernel _Z14fwd_megakernel6Params
		.amdhsa_group_segment_fixed_size 0
		.amdhsa_private_segment_fixed_size 0
		.amdhsa_kernarg_size 440
		.amdhsa_user_sgpr_count 2
		.amdhsa_user_sgpr_dispatch_ptr 0
		.amdhsa_user_sgpr_queue_ptr 0
		.amdhsa_user_sgpr_kernarg_segment_ptr 1
		.amdhsa_user_sgpr_dispatch_id 0
		.amdhsa_user_sgpr_kernarg_preload_length 0
		.amdhsa_user_sgpr_kernarg_preload_offset 0
		.amdhsa_user_sgpr_private_segment_size 0
		.amdhsa_uses_dynamic_stack 0
		.amdhsa_enable_private_segment 0
		.amdhsa_system_sgpr_workgroup_id_x 1
		.amdhsa_system_sgpr_workgroup_id_y 0
		.amdhsa_system_sgpr_workgroup_id_z 0
		.amdhsa_system_sgpr_workgroup_info 0
		.amdhsa_system_vgpr_workitem_id 0
		.amdhsa_next_free_vgpr 256
		.amdhsa_next_free_sgpr 102
		.amdhsa_accum_offset 256
		.amdhsa_reserve_vcc 1
		.amdhsa_float_round_mode_32 0
		.amdhsa_float_round_mode_16_64 0
		.amdhsa_float_denorm_mode_32 3
		.amdhsa_float_denorm_mode_16_64 3
		.amdhsa_dx10_clamp 1
		.amdhsa_ieee_mode 1
		.amdhsa_fp16_overflow 0
		.amdhsa_tg_split 0
		.amdhsa_exception_fp_ieee_invalid_op 0
		.amdhsa_exception_fp_denorm_src 0
		.amdhsa_exception_fp_ieee_div_zero 0
		.amdhsa_exception_fp_ieee_overflow 0
		.amdhsa_exception_fp_ieee_underflow 0
		.amdhsa_exception_fp_ieee_inexact 0
		.amdhsa_exception_int_div_zero 0
	.end_amdhsa_kernel

amdhsa.kernels:
  - .agpr_count:     0
    .args:
      - .offset:         0
        .size:           184
        .value_kind:     by_value
      - .offset:         184
        .size:           4
        .value_kind:     hidden_block_count_x
      - .offset:         188
        .size:           4
        .value_kind:     hidden_block_count_y
      - .offset:         192
        .size:           4
        .value_kind:     hidden_block_count_z
      - .offset:         196
        .size:           2
        .value_kind:     hidden_group_size_x
      - .offset:         198
        .size:           2
        .value_kind:     hidden_group_size_y
      - .offset:         200
        .size:           2
        .value_kind:     hidden_group_size_z
      - .offset:         202
        .size:           2
        .value_kind:     hidden_remainder_x
      - .offset:         204
        .size:           2
        .value_kind:     hidden_remainder_y
      - .offset:         206
        .size:           2
        .value_kind:     hidden_remainder_z
      - .offset:         224
        .size:           8
        .value_kind:     hidden_global_offset_x
      - .offset:         232
        .size:           8
        .value_kind:     hidden_global_offset_y
      - .offset:         240
        .size:           8
        .value_kind:     hidden_global_offset_z
      - .offset:         248
        .size:           2
        .value_kind:     hidden_grid_dims
      - .offset:         304
        .size:           4
        .value_kind:     hidden_dynamic_lds_size
    .group_segment_fixed_size: 0
    .kernarg_segment_align: 8
    .kernarg_segment_size: 440
    .language:       OpenCL C
    .language_version:
      - 2
      - 0
    .max_flat_workgroup_size: 512
    .name:           _Z14fwd_megakernel6Params
    .private_segment_fixed_size: 0
    .sgpr_count:     108
    .sgpr_spill_count: 148
    .symbol:         _Z14fwd_megakernel6Params.kd
    .uniform_work_group_size: 1
    .uses_dynamic_stack: false
    .vgpr_count:     256
    .vgpr_spill_count: 0
    .wavefront_size: 64
